# lnv: cross-iteration prefetch - next iteration's 8 row loads issued right after the current iteration's ushort block; top prefetch only for the first iteration
# baseline (speedup 1.0000x reference)
.LBB0_177:
	v_lshl_add_u64 v[66:67], v[34:35], 0, s[8:9]
	s_cmp_lg_u32 s8, 0
	s_cbranch_scc1 .Llnv_pfd
	s_branch .Llnv_pf

.Llnv_usd:
	v_add_co_u32_e32 v76, vcc, s80, v50
	s_waitcnt lgkmcnt(0)
	v_add_f32_e32 v70, v21, v11
	v_addc_co_u32_e32 v77, vcc, 0, v51, vcc
	v_add_co_u32_e32 v76, vcc, s81, v50
	v_cndmask_b32_e64 v72, v72, v78, s[40:41]
	s_nop 0
	v_addc_co_u32_e32 v77, vcc, 0, v51, vcc
	v_add_co_u32_e32 v76, vcc, s91, v50
	ds_bpermute_b32 v11, v250, v23
	s_nop 0
	v_addc_co_u32_e32 v77, vcc, 0, v51, vcc
	v_add_co_u32_e32 v76, vcc, s11, v50
	s_waitcnt lgkmcnt(0)
	v_add_f32_e32 v68, v23, v11
	v_addc_co_u32_e32 v77, vcc, 0, v51, vcc
	v_add_co_u32_e32 v80, vcc, s80, v48
	ds_bpermute_b32 v11, v250, v65
	s_nop 0
	v_addc_co_u32_e32 v81, vcc, 0, v49, vcc
	v_mov_b32_e32 v143, v62
	v_pk_mul_f32 v[70:71], v[70:71], v[142:143]
	s_waitcnt lgkmcnt(0)
	v_add_f32_e32 v66, v65, v11
	ds_bpermute_b32 v11, v250, v64
	v_mov_b32_e32 v143, v63
	v_pk_mul_f32 v[68:69], v[68:69], v[142:143]
	v_mov_b32_e32 v143, v60
	v_pk_mul_f32 v[66:67], v[66:67], v[142:143]
	s_waitcnt lgkmcnt(0)
	v_add_f32_e32 v64, v64, v11
	v_mov_b32_e32 v65, v61
	v_mov_b32_e32 v143, v61
	v_pk_mul_f32 v[64:65], v[64:65], v[142:143]
	v_add_u32_e32 v11, 0x4200, v9
	s_waitcnt vmcnt(23)
	v_mov_b32_e32 v13, v150
	v_lshlrev_b32_e32 v78, 16, v13
	v_add_co_u32_e32 v80, vcc, s81, v48
	s_waitcnt vmcnt(22)
	v_mov_b32_e32 v15, v151
	v_lshlrev_b32_e32 v79, 16, v15
	v_addc_co_u32_e32 v81, vcc, 0, v49, vcc
	v_add_co_u32_e32 v80, vcc, s91, v48
	s_waitcnt vmcnt(21)
	v_mov_b32_e32 v19, v152
	v_lshlrev_b32_e32 v76, 16, v19
	v_addc_co_u32_e32 v81, vcc, 0, v49, vcc
	v_add_co_u32_e32 v80, vcc, s11, v48
	s_waitcnt vmcnt(20)
	v_mov_b32_e32 v21, v153
	v_lshlrev_b32_e32 v77, 16, v21
	v_addc_co_u32_e32 v81, vcc, 0, v49, vcc
	v_pk_fma_f32 v[78:79], v[56:57], s[26:27], v[78:79] op_sel_hi:[1,0,1] neg_lo:[1,0,0] neg_hi:[1,0,0]
	v_pk_fma_f32 v[76:77], v[52:53], s[26:27], v[76:77] op_sel_hi:[1,0,1] neg_lo:[1,0,0] neg_hi:[1,0,0]
	v_pk_mul_f32 v[78:79], v[78:79], v[72:73]
	v_pk_mul_f32 v[76:77], v[76:77], v[74:75]
	v_pk_fma_f32 v[78:79], v[42:43], v[78:79], v[40:41]
	v_pk_fma_f32 v[76:77], v[28:29], v[76:77], v[24:25]
	s_waitcnt vmcnt(19)
	v_mov_b32_e32 v13, v154
	v_lshlrev_b32_e32 v82, 16, v13
	v_sub_f32_e32 v13, v70, v71
	v_max_f32_e32 v62, 0, v13
	v_sub_f32_e32 v13, v68, v69
	v_max_f32_e32 v63, 0, v13
	v_sub_f32_e32 v13, v66, v67
	v_max_f32_e32 v60, 0, v13
	v_sub_f32_e32 v13, v64, v65
	v_pk_add_f32 v[62:63], v[62:63], s[22:23] op_sel_hi:[1,0]
	v_max_f32_e32 v61, 0, v13
	v_mul_f32_e32 v13, 0x4b800000, v62
	v_cmp_gt_f32_e64 s[44:45], s86, v62
	v_cmp_gt_f32_e64 s[42:43], s86, v63
	v_pk_add_f32 v[60:61], v[60:61], s[22:23] op_sel_hi:[1,0]
	v_cndmask_b32_e64 v13, v62, v13, s[44:45]
	v_rsq_f32_e32 v62, v13
	v_mul_f32_e32 v13, 0x4b800000, v63
	v_cndmask_b32_e64 v13, v63, v13, s[42:43]
	v_cmp_gt_f32_e64 s[40:41], s86, v60
	v_rsq_f32_e32 v63, v13
	v_mul_f32_e32 v13, 0x4b800000, v60
	v_cndmask_b32_e64 v13, v60, v13, s[40:41]
	v_cmp_gt_f32_e32 vcc, s86, v61
	v_rsq_f32_e32 v60, v13
	v_mul_f32_e32 v13, 0x4b800000, v61
	v_cndmask_b32_e32 v13, v61, v13, vcc
	v_rsq_f32_e32 v61, v13
	v_pk_mul_f32 v[64:65], v[62:63], s[10:11] op_sel_hi:[1,0]
	s_waitcnt vmcnt(18)
	v_mov_b32_e32 v15, v155
	v_lshlrev_b32_e32 v83, 16, v15
	v_cndmask_b32_e64 v62, v62, v64, s[44:45]
	v_pk_mul_f32 v[66:67], v[60:61], s[10:11] op_sel_hi:[1,0]
	v_cndmask_b32_e64 v63, v63, v65, s[42:43]
	v_cndmask_b32_e32 v61, v61, v67, vcc
	v_add_co_u32_e32 v64, vcc, s84, v50
	v_cndmask_b32_e64 v60, v60, v66, s[40:41]
	s_nop 0
	v_addc_co_u32_e32 v65, vcc, 0, v51, vcc
	v_add_co_u32_e32 v64, vcc, s85, v50
	s_waitcnt vmcnt(16)
	v_mov_b32_e32 v19, v156
	v_mov_b32_e32 v21, v157
	v_lshlrev_b32_e32 v81, 16, v21
	v_addc_co_u32_e32 v65, vcc, 0, v51, vcc
	v_add_co_u32_e32 v64, vcc, s82, v50
	v_lshlrev_b32_e32 v80, 16, v19
	s_nop 0
	v_addc_co_u32_e32 v65, vcc, 0, v51, vcc
	v_add_co_u32_e32 v50, vcc, s83, v50
	s_nop 0
	v_addc_co_u32_e32 v51, vcc, 0, v51, vcc
	v_add_co_u32_e32 v66, vcc, s84, v48
	v_pk_fma_f32 v[56:57], v[56:57], s[26:27], v[82:83] op_sel_hi:[1,0,1] neg_lo:[1,0,0] neg_hi:[1,0,0]
	s_nop 0
	v_addc_co_u32_e32 v67, vcc, 0, v49, vcc
	v_pk_fma_f32 v[52:53], v[52:53], s[26:27], v[80:81] op_sel_hi:[1,0,1] neg_lo:[1,0,0] neg_hi:[1,0,0]
	v_pk_mul_f32 v[56:57], v[56:57], v[72:73]
	v_pk_mul_f32 v[52:53], v[52:53], v[74:75]
	v_pk_fma_f32 v[56:57], v[46:47], v[56:57], v[44:45]
	v_pk_fma_f32 v[52:53], v[26:27], v[52:53], v[32:33]
	s_waitcnt vmcnt(15)
	v_mov_b32_e32 v13, v158
	v_lshlrev_b32_e32 v64, 16, v13
	v_add_co_u32_e32 v66, vcc, s85, v48
	s_waitcnt vmcnt(14)
	v_mov_b32_e32 v15, v159
	v_lshlrev_b32_e32 v65, 16, v15
	v_addc_co_u32_e32 v67, vcc, 0, v49, vcc
	v_add_co_u32_e32 v66, vcc, s82, v48
	v_pk_fma_f32 v[64:65], v[58:59], s[26:27], v[64:65] op_sel_hi:[1,0,1] neg_lo:[1,0,0] neg_hi:[1,0,0]
	s_nop 0
	v_addc_co_u32_e32 v67, vcc, 0, v49, vcc
	v_add_co_u32_e32 v48, vcc, s83, v48
	s_waitcnt vmcnt(12)
	v_mov_b32_e32 v19, v160
	v_mov_b32_e32 v21, v161
	v_lshlrev_b32_e32 v51, 16, v21
	v_addc_co_u32_e32 v49, vcc, 0, v49, vcc
	v_lshlrev_b32_e32 v50, 16, v19
	v_pk_fma_f32 v[50:51], v[54:55], s[26:27], v[50:51] op_sel_hi:[1,0,1] neg_lo:[1,0,0] neg_hi:[1,0,0]
	v_pk_mul_f32 v[64:65], v[64:65], v[60:61]
	v_pk_mul_f32 v[50:51], v[50:51], v[62:63]
	v_pk_fma_f32 v[64:65], v[42:43], v[64:65], v[40:41]
	v_pk_fma_f32 v[50:51], v[28:29], v[50:51], v[24:25]
	v_cvt_pk_bf16_f32 v65, v64, v65
	v_cvt_pk_bf16_f32 v64, v50, v51
	v_cvt_pk_bf16_f32 v51, v78, v79
	v_cvt_pk_bf16_f32 v50, v76, v77
	ds_write2_b64 v9, v[50:51], v[64:65] offset1:1
	v_add_u32_e32 v9, 16, v9
	s_waitcnt vmcnt(11)
	v_mov_b32_e32 v13, v162
	v_lshlrev_b32_e32 v50, 16, v13
	s_waitcnt vmcnt(10)
	v_mov_b32_e32 v15, v163
	v_lshlrev_b32_e32 v51, 16, v15
	v_pk_fma_f32 v[50:51], v[58:59], s[26:27], v[50:51] op_sel_hi:[1,0,1] neg_lo:[1,0,0] neg_hi:[1,0,0]
	s_waitcnt vmcnt(9)
	v_mov_b32_e32 v19, v164
	v_lshlrev_b32_e32 v48, 16, v19
	s_waitcnt vmcnt(8)
	v_mov_b32_e32 v21, v165
	v_lshlrev_b32_e32 v49, 16, v21
	v_pk_fma_f32 v[48:49], v[54:55], s[26:27], v[48:49] op_sel_hi:[1,0,1] neg_lo:[1,0,0] neg_hi:[1,0,0]
	v_pk_mul_f32 v[50:51], v[50:51], v[60:61]
	v_pk_mul_f32 v[48:49], v[48:49], v[62:63]
	v_pk_fma_f32 v[50:51], v[46:47], v[50:51], v[44:45]
	v_pk_fma_f32 v[48:49], v[26:27], v[48:49], v[32:33]
	v_cvt_pk_bf16_f32 v51, v50, v51
	v_cvt_pk_bf16_f32 v50, v48, v49
	v_cvt_pk_bf16_f32 v49, v56, v57
	v_cvt_pk_bf16_f32 v48, v52, v53
	ds_write2_b64 v11, v[48:49], v[50:51] offset1:1
	s_cbranch_scc0 .LBB0_177
	s_waitcnt vmcnt(0)
	v_mul_u32_u24_e32 v128, 0x180, v7
	v_lshl_add_u64 v[24:25], v[128:129], 0, v[30:31]
	v_lshlrev_b64 v[24:25], 15, v[24:25]
	s_waitcnt lgkmcnt(0)
	s_barrier
	v_lshl_add_u64 v[28:29], v[0:1], 0, v[24:25]
	ds_read2_b64 v[24:27], v90 offset1:1
	v_mov_b32_e32 v7, v129
	v_lshl_add_u64 v[30:31], v[28:29], 0, v[6:7]
	v_mov_b32_e32 v9, v129
	v_mov_b32_e32 v11, v129
	s_waitcnt lgkmcnt(0)
	global_store_dwordx4 v[30:31], v[24:27], off
	ds_read2_b64 v[24:27], v91 offset1:1
	v_lshl_add_u64 v[30:31], v[28:29], 0, v[8:9]
	v_mov_b32_e32 v13, v129
	v_mov_b32_e32 v15, v129
	v_mov_b32_e32 v19, v129
	s_waitcnt lgkmcnt(0)
	global_store_dwordx4 v[30:31], v[24:27], off
	ds_read2_b64 v[24:27], v92 offset1:1
	v_lshl_add_u64 v[30:31], v[28:29], 0, v[10:11]
	v_mov_b32_e32 v21, v129
	v_add_u32_e32 v98, s23, v98
	s_movk_i32 s0, 0x5ff
	s_waitcnt lgkmcnt(0)
	global_store_dwordx4 v[30:31], v[24:27], off
	ds_read2_b64 v[24:27], v93 offset1:1
	v_lshl_add_u64 v[30:31], v[28:29], 0, v[12:13]
	v_mov_b32_e32 v23, v129
	v_cmp_lt_i32_e32 vcc, s0, v98
	v_subrev_u16_e32 v88, s23, v88
	s_waitcnt lgkmcnt(0)
	global_store_dwordx4 v[30:31], v[24:27], off
	ds_read2_b64 v[24:27], v94 offset1:1
	v_lshl_add_u64 v[30:31], v[28:29], 0, v[14:15]
	s_or_b64 s[12:13], vcc, s[12:13]
	s_waitcnt lgkmcnt(0)
	global_store_dwordx4 v[30:31], v[24:27], off
	ds_read2_b64 v[24:27], v95 offset1:1
	v_lshl_add_u64 v[30:31], v[28:29], 0, v[18:19]
	s_waitcnt lgkmcnt(0)
	global_store_dwordx4 v[30:31], v[24:27], off
	ds_read2_b64 v[24:27], v96 offset1:1
	v_lshl_add_u64 v[30:31], v[28:29], 0, v[20:21]
	v_lshl_add_u64 v[28:29], v[28:29], 0, v[22:23]
	s_waitcnt lgkmcnt(0)
	global_store_dwordx4 v[30:31], v[24:27], off
	ds_read2_b64 v[24:27], v97 offset1:1
	s_waitcnt lgkmcnt(0)
	global_store_dwordx4 v[28:29], v[24:27], off
	s_barrier
	s_andn2_b64 exec, exec, s[12:13]
	s_cbranch_execnz .LBB0_176
	s_or_b64 exec, exec, s[12:13]

.Lnm_pro:
	v_lshl_add_u64 v[112:113], s[88:89], 0, v[36:37]
	v_lshl_add_u64 v[114:115], s[88:89], 0, v[58:59]
	v_add_co_u32_e32 v112, vcc, 0x8a80000, v112
	s_nop 0
	v_addc_co_u32_e32 v113, vcc, 0, v113, vcc
	global_load_dwordx4 v[0:3], v[114:115], off
	global_load_dwordx4 v[4:7], v[114:115], off offset:1024
	global_load_dwordx4 v[8:11], v[112:113], off
	global_load_dwordx4 v[12:15], v[112:113], off offset:1024
	s_branch .LBB0_318
	s_nop 0
	s_nop 0
	s_nop 0
	s_nop 0
	s_nop 0
	s_nop 0
	s_nop 0
	s_nop 0
	s_nop 0
	s_nop 0
	s_nop 0
	s_nop 0
	s_nop 0
	s_nop 0
	s_nop 0
	s_nop 0
	s_nop 0
	s_nop 0
	s_nop 0
	s_nop 0
	s_nop 0
	s_nop 0
	s_nop 0
	s_nop 0
	s_nop 0
	s_nop 0
	s_nop 0
	s_nop 0
	s_nop 0
	s_nop 0
	s_nop 0
	s_nop 0
	s_nop 0
	s_nop 0
	s_nop 0
	s_nop 0
	s_nop 0
	s_nop 0
	s_nop 0
	s_nop 0
	s_nop 0
	s_nop 0
	s_nop 0
	s_nop 0
	s_nop 0
	s_nop 0
	s_nop 0
	s_nop 0
	s_nop 0
	s_nop 0
	s_nop 0
	s_nop 0
	s_nop 0
	s_nop 0
	s_nop 0
	s_nop 0
	s_nop 0
	s_nop 0
	s_nop 0
	s_nop 0
	s_nop 0
	s_nop 0
	s_nop 0
	s_nop 0
	s_nop 0
	s_nop 0
	s_nop 0
	s_nop 0
	s_nop 0
	s_nop 0
	s_nop 0
	s_nop 0
	s_nop 0
	s_nop 0
	s_nop 0
	s_nop 0
	s_nop 0
	s_nop 0
	s_nop 0
	s_nop 0
	s_nop 0
	s_nop 0
	s_nop 0
	s_nop 0
	s_nop 0
	s_nop 0
	s_nop 0
	s_nop 0
	s_nop 0
	s_nop 0
	s_nop 0
	s_nop 0
	s_nop 0
	s_nop 0
	s_nop 0
	s_nop 0
	s_nop 0
	s_nop 0
	s_nop 0
	s_nop 0
	s_nop 0
	s_nop 0
	s_nop 0
	s_nop 0
	s_nop 0
	s_nop 0
	s_nop 0
	s_nop 0
	s_nop 0
	s_nop 0
	s_nop 0
	s_nop 0
	s_nop 0
	s_nop 0
	s_nop 0
	s_nop 0
	s_nop 0
	s_nop 0
	s_nop 0
	s_nop 0
	s_nop 0
	s_nop 0
	s_nop 0
	s_nop 0
	s_nop 0
	s_nop 0
	s_nop 0
	s_nop 0
	s_nop 0
	s_nop 0
	s_nop 0
	s_nop 0
	s_nop 0
	s_nop 0
	s_nop 0
	s_nop 0
	s_nop 0
	s_nop 0
	s_nop 0
	s_nop 0
	s_nop 0
	s_nop 0
	s_nop 0
	s_nop 0
	s_nop 0
	s_nop 0
	s_nop 0
	s_nop 0
	s_nop 0
	s_nop 0
	s_nop 0
	s_nop 0
	s_nop 0
	s_nop 0
	s_nop 0
	s_nop 0
	s_nop 0
	s_nop 0
	s_nop 0
	s_nop 0
	s_nop 0
	s_nop 0
	s_nop 0
	s_nop 0
	s_nop 0
	s_nop 0
	s_nop 0
	s_nop 0
	s_nop 0
	s_nop 0
	s_nop 0
	s_nop 0
	s_nop 0
	s_nop 0
	s_nop 0
	s_nop 0
	s_nop 0
	s_nop 0
	s_nop 0
	s_nop 0
	s_nop 0
	s_nop 0
	s_nop 0
	s_nop 0
	s_nop 0
	s_nop 0
	s_nop 0
	s_nop 0
	s_nop 0
	s_nop 0
	s_nop 0
	s_nop 0
	s_nop 0
	s_nop 0
	s_nop 0
	s_nop 0
	s_nop 0
	s_nop 0
	s_nop 0
	s_nop 0
	s_nop 0
	s_nop 0
	s_nop 0
	s_nop 0
	s_nop 0
	s_nop 0
	s_nop 0
	s_nop 0
	s_nop 0
	s_nop 0
	s_nop 0
	s_nop 0
	s_nop 0
	s_nop 0
	s_nop 0
	s_nop 0
	s_nop 0
	s_nop 0
	s_nop 0
	s_nop 0
	s_nop 0
	s_nop 0
	s_nop 0
	s_nop 0
	s_nop 0
	s_nop 0
	s_nop 0
	s_nop 0
	s_nop 0
	s_nop 0
	s_nop 0
	s_nop 0
	s_nop 0
	s_nop 0
	s_nop 0
	s_nop 0
	s_nop 0
	s_nop 0
	s_nop 0
	s_nop 0
	s_nop 0
	s_nop 0
	s_nop 0
	s_nop 0
	s_nop 0
	s_nop 0
	s_nop 0
	s_nop 0
	s_nop 0
.Lfbp_addr:
	v_alignbit_b32 v212, v191, v190, 2
	v_add_u32_e32 v214, v201, v212
	v_ashrrev_i32_e32 v215, 31, v214
	v_lshlrev_b64 v[236:237], 11, v[214:215]
	v_lshl_add_u64 v[236:237], s[6:7], 0, v[236:237]
	v_lshl_add_u64 v[236:237], v[236:237], 0, v[128:129]
	v_add_u32_e32 v214, v202, v212
	v_ashrrev_i32_e32 v215, 31, v214
	v_lshlrev_b64 v[238:239], 11, v[214:215]
	v_lshl_add_u64 v[238:239], s[6:7], 0, v[238:239]
	v_lshl_add_u64 v[238:239], v[238:239], 0, v[128:129]
	v_mbcnt_lo_u32_b32 v220, -1, 0
	v_mbcnt_hi_u32_b32 v220, -1, v220
	v_and_b32_e32 v220, 32, v220
	v_lshrrev_b32_e32 v220, 2, v220
	v_mov_b32_e32 v221, 0
	v_lshl_add_u64 v[236:237], v[236:237], 0, v[220:221]
	v_lshl_add_u64 v[238:239], v[238:239], 0, v[220:221]
	s_branch .Lfbp_addrd

.Llnv_us:
	v_add_co_u32_e32 v166, vcc, s80, v50
	s_nop 0
	v_addc_co_u32_e32 v167, vcc, 0, v51, vcc
	global_load_ushort v150, v[166:167], off offset:1024
	v_add_co_u32_e32 v166, vcc, s81, v50
	s_nop 0
	v_addc_co_u32_e32 v167, vcc, 0, v51, vcc
	global_load_ushort v151, v[166:167], off offset:1024
	v_add_co_u32_e32 v166, vcc, s91, v50
	s_nop 0
	v_addc_co_u32_e32 v167, vcc, 0, v51, vcc
	global_load_ushort v152, v[166:167], off offset:1024
	v_add_co_u32_e32 v166, vcc, s11, v50
	s_nop 0
	v_addc_co_u32_e32 v167, vcc, 0, v51, vcc
	global_load_ushort v153, v[166:167], off offset:1024
	v_add_co_u32_e32 v166, vcc, s80, v48
	s_nop 0
	v_addc_co_u32_e32 v167, vcc, 0, v49, vcc
	global_load_ushort v154, v[166:167], off offset:1024
	v_add_co_u32_e32 v166, vcc, s81, v48
	s_nop 0
	v_addc_co_u32_e32 v167, vcc, 0, v49, vcc
	global_load_ushort v155, v[166:167], off offset:1024
	v_add_co_u32_e32 v166, vcc, s91, v48
	s_nop 0
	v_addc_co_u32_e32 v167, vcc, 0, v49, vcc
	global_load_ushort v156, v[166:167], off offset:1024
	v_add_co_u32_e32 v166, vcc, s11, v48
	s_nop 0
	v_addc_co_u32_e32 v167, vcc, 0, v49, vcc
	global_load_ushort v157, v[166:167], off offset:1024
	v_add_co_u32_e32 v166, vcc, s84, v50
	s_nop 0
	v_addc_co_u32_e32 v167, vcc, 0, v51, vcc
	global_load_ushort v158, v[166:167], off offset:1024
	v_add_co_u32_e32 v166, vcc, s85, v50
	s_nop 0
	v_addc_co_u32_e32 v167, vcc, 0, v51, vcc
	global_load_ushort v159, v[166:167], off offset:1024
	v_add_co_u32_e32 v166, vcc, s82, v50
	s_nop 0
	v_addc_co_u32_e32 v167, vcc, 0, v51, vcc
	global_load_ushort v160, v[166:167], off offset:1024
	v_add_co_u32_e32 v166, vcc, s83, v50
	s_nop 0
	v_addc_co_u32_e32 v167, vcc, 0, v51, vcc
	global_load_ushort v161, v[166:167], off offset:1024
	v_add_co_u32_e32 v166, vcc, s84, v48
	s_nop 0
	v_addc_co_u32_e32 v167, vcc, 0, v49, vcc
	global_load_ushort v162, v[166:167], off offset:1024
	v_add_co_u32_e32 v166, vcc, s85, v48
	s_nop 0
	v_addc_co_u32_e32 v167, vcc, 0, v49, vcc
	global_load_ushort v163, v[166:167], off offset:1024
	v_add_co_u32_e32 v166, vcc, s82, v48
	s_nop 0
	v_addc_co_u32_e32 v167, vcc, 0, v49, vcc
	global_load_ushort v164, v[166:167], off offset:1024
	v_add_co_u32_e32 v166, vcc, s83, v48
	s_nop 0
	v_addc_co_u32_e32 v167, vcc, 0, v49, vcc
	global_load_ushort v165, v[166:167], off offset:1024
	v_lshl_add_u64 v[168:169], v[34:35], 0, s[8:9]
	v_add_co_u32_e32 v136, vcc, 0xea80000, v168
	s_nop 0
	v_addc_co_u32_e32 v137, vcc, 0, v169, vcc
	global_load_dwordx4 v[100:103], v[136:137], off offset:1024
	v_add_co_u32_e32 v136, vcc, 0xea81000, v168
	s_nop 0
	v_addc_co_u32_e32 v137, vcc, 0, v169, vcc
	global_load_dwordx4 v[104:107], v[136:137], off offset:1024
	v_add_co_u32_e32 v136, vcc, s80, v168
	s_nop 0
	v_addc_co_u32_e32 v137, vcc, 0, v169, vcc
	global_load_dwordx4 v[108:111], v[136:137], off offset:1024
	v_add_co_u32_e32 v136, vcc, s81, v168
	s_nop 0
	v_addc_co_u32_e32 v137, vcc, 0, v169, vcc
	global_load_dwordx4 v[112:115], v[136:137], off offset:1024
	v_add_co_u32_e32 v136, vcc, s82, v168
	s_nop 0
	v_addc_co_u32_e32 v137, vcc, 0, v169, vcc
	global_load_dwordx4 v[116:119], v[136:137], off offset:1024
	v_add_co_u32_e32 v136, vcc, s83, v168
	s_nop 0
	v_addc_co_u32_e32 v137, vcc, 0, v169, vcc
	global_load_dwordx4 v[120:123], v[136:137], off offset:1024
	v_add_co_u32_e32 v136, vcc, s84, v168
	s_nop 0
	v_addc_co_u32_e32 v137, vcc, 0, v169, vcc
	global_load_dwordx4 v[124:127], v[136:137], off offset:1024
	v_add_co_u32_e32 v136, vcc, s85, v168
	s_nop 0
	v_addc_co_u32_e32 v137, vcc, 0, v169, vcc
	global_load_dwordx4 v[132:135], v[136:137], off offset:1024
	s_branch .Llnv_usd
